# v32: v31 + P5 step 6 (o += A V): six LDS fragment reads in flight together
# baseline (speedup 1.0000x reference)
; #define LAS __attribute__((address_space(3)))
; DI unsigned pk2(float lo, float hi) { f32x2 v = {lo, hi}; bfv2 b = __builtin_convertvector(v, bfv2); return __builtin_bit_cast(unsigned, b); }
; DI bf16_t f2bf(float x) { return (bf16_t)(pk2(x, 0.f) & 0xffffu); }
; #define MFMA16(a, b, c) __builtin_amdgcn_mfma_f32_16x16x32_bf16((a), (b), (c), 0, 0, 0)
; template <bool OUT> DI void hgrn_item(LAS unsigned char* lds, bf16_t* proj, float* hst, float* hdv, const float* normw, int item, bool dry) {
;     ...
;                 for (int r = 0; r < 4; ++r) { const int tt = 16 * ti + 4 * rq + r, ss = 16 * sj + e16; Ab[tt * TP + ss] = (sj <= ti && ss <= tt) ? f2bf(a[r]) : (bf16_t)0; }
;             }
; #pragma unroll
;             for (int ti = 0; ti < 4; ++ti) { o[ti] = (f32x4){0.f, 0.f, 0.f, 0.f};
; #pragma unroll
;                 for (int ks = 0; ks < 4; ++ks) { const LAS bf16_t* qp = Qt + (16 * ti + e16) * QP + 32 * ks + 4 * rq; const u32x2 q0 = *(const LAS u32x2*)qp, q1 = *(const LAS u32x2*)(qp + 16);
;                     u32x4 qa = {q0.x, q0.y, q1.x, q1.y};
;                     u32x4 sb; sb.x = pk2(st[2 * ks][0], st[2 * ks][1]); sb.y = pk2(st[2 * ks][2], st[2 * ks][3]); sb.z = pk2(st[2 * ks + 1][0], st[2 * ks + 1][1]); sb.w = pk2(st[2 * ks + 1][2], st[2 * ks + 1][3]);
;                     o[ti] = MFMA16(__builtin_bit_cast(bf16x8, qa), __builtin_bit_cast(bf16x8, sb), o[ti]); } }
;         }
; #pragma unroll
;         for (int dt = 0; dt < 8; ++dt) {
; #pragma unroll
;             for (int ks = 0; ks < 2; ++ks) { const bf16x8 ka = *(const LAS bf16x8*)(KtT + (16 * dt + e16) * TP + 32 * ks + 8 * rq); st[dt] = MFMA16(ka, vfr[ks], st[dt]); }
;             const f32x4 dv = *(const LAS f32x4*)(Dv + 16 * dt + 4 * rq);
;             st[dt] *= dv;
;         }
.LBB0_1170:
	v_or_b32_e32 v56, s14, v104
	v_cmp_gt_u32_e32 vcc, v120, v56
	s_or_b64 s[36:37], s[20:21], vcc
	s_nop 3
	v_cvt_pk_bf16_f32 v50, v50, s0
	v_cndmask_b32_e64 v50, v50, 0, s[36:37]
	v_mad_u64_u32 v[54:55], s[36:37], v56, s39, v[92:93]
	ds_write_b16 v54, v50
	v_or_b32_e32 v50, 1, v56
	v_cmp_gt_u32_e32 vcc, v120, v50
	s_or_b64 s[36:37], s[20:21], vcc
	v_cvt_pk_bf16_f32 v50, v51, s0
	v_cndmask_b32_e64 v50, v50, 0, s[36:37]
	ds_write_b16 v54, v50 offset:144
	v_or_b32_e32 v50, 2, v56
	v_cmp_gt_u32_e32 vcc, v120, v50
	s_or_b64 s[36:37], s[20:21], vcc
	v_cvt_pk_bf16_f32 v50, v52, s0
	v_cndmask_b32_e64 v50, v50, 0, s[36:37]
	ds_write_b16 v54, v50 offset:288
	v_or_b32_e32 v50, 3, v56
	v_cmp_gt_u32_e32 vcc, v120, v50
	s_or_b64 s[36:37], s[20:21], vcc
	v_cvt_pk_bf16_f32 v50, v53, s0
	v_cndmask_b32_e64 v50, v50, 0, s[36:37]
	ds_write_b16 v54, v50 offset:432
	ds_read2_b64 v[50:53], v115 offset1:4
	ds_read2_b64 v[54:57], v115 offset0:8 offset1:12
	s_waitcnt vmcnt(7)
	v_cvt_pk_bf16_f32 v66, v6, v7
	v_cvt_pk_bf16_f32 v67, v8, v9
	s_waitcnt vmcnt(6)
	v_cvt_pk_bf16_f32 v68, v10, v11
	v_cvt_pk_bf16_f32 v69, v12, v13
	s_waitcnt vmcnt(5)
	v_cvt_pk_bf16_f32 v70, v2, v3
	v_cvt_pk_bf16_f32 v71, v4, v5
	s_waitcnt lgkmcnt(1)
	v_mfma_f32_16x16x32_bf16 v[50:53], v[50:53], v[66:69], 0
	s_waitcnt vmcnt(4)
	v_cvt_pk_bf16_f32 v72, v18, v19
	v_cvt_pk_bf16_f32 v73, v20, v21
	s_waitcnt vmcnt(3)
	v_cvt_pk_bf16_f32 v100, v14, v15
	v_cvt_pk_bf16_f32 v101, v16, v17
	s_waitcnt lgkmcnt(0)
	v_mfma_f32_16x16x32_bf16 v[50:53], v[54:57], v[70:73], v[50:53]
	ds_read2_b64 v[54:57], v115 offset0:16 offset1:20
	s_waitcnt vmcnt(2)
	v_cvt_pk_bf16_f32 v102, v26, v27
	v_cvt_pk_bf16_f32 v103, v28, v29
	s_waitcnt vmcnt(1)
	v_cvt_pk_bf16_f32 v144, v22, v23
	v_cvt_pk_bf16_f32 v145, v24, v25
	s_waitcnt lgkmcnt(0)
	v_mfma_f32_16x16x32_bf16 v[50:53], v[54:57], v[100:103], v[50:53]
	ds_read2_b64 v[54:57], v115 offset0:24 offset1:28
	s_waitcnt vmcnt(0)
	v_cvt_pk_bf16_f32 v146, v30, v31
	v_cvt_pk_bf16_f32 v147, v32, v33
	v_add_u32_e32 v62, 0x1000, v115
	ds_read2_b64 v[58:61], v62 offset0:40 offset1:44
	s_waitcnt lgkmcnt(1)
	v_mfma_f32_16x16x32_bf16 v[54:57], v[54:57], v[144:147], v[50:53]
	s_nop 2
	ds_read2_b64 v[50:53], v62 offset0:32 offset1:36
	v_add_u32_e32 v143, 0x2000, v115
	s_waitcnt lgkmcnt(0)
	v_mfma_f32_16x16x32_bf16 v[50:53], v[50:53], v[66:69], 0
	v_mfma_f32_16x16x32_bf16 v[50:53], v[58:61], v[70:73], v[50:53]
	ds_read2_b64 v[58:61], v62 offset0:48 offset1:52
	s_waitcnt lgkmcnt(0)
	v_mfma_f32_16x16x32_bf16 v[50:53], v[58:61], v[100:103], v[50:53]
	ds_read2_b64 v[58:61], v62 offset0:56 offset1:60
	ds_read2_b64 v[62:65], v143 offset0:72 offset1:76
	s_waitcnt lgkmcnt(1)
	v_mfma_f32_16x16x32_bf16 v[58:61], v[58:61], v[144:147], v[50:53]
	s_nop 3
	ds_read2_b64 v[50:53], v143 offset0:64 offset1:68
	s_waitcnt lgkmcnt(0)
	v_mfma_f32_16x16x32_bf16 v[50:53], v[50:53], v[66:69], 0
	v_mfma_f32_16x16x32_bf16 v[50:53], v[62:65], v[70:73], v[50:53]
	ds_read2_b64 v[62:65], v143 offset0:80 offset1:84
	s_waitcnt lgkmcnt(0)
	v_mfma_f32_16x16x32_bf16 v[50:53], v[62:65], v[100:103], v[50:53]
	ds_read2_b64 v[62:65], v143 offset0:88 offset1:92
	v_add_u32_e32 v143, 0x3000, v115
	s_waitcnt lgkmcnt(0)
	v_mfma_f32_16x16x32_bf16 v[62:65], v[62:65], v[144:147], v[50:53]
	s_nop 3
	ds_read2_b64 v[50:53], v143 offset0:96 offset1:100
	s_waitcnt lgkmcnt(0)
	v_mfma_f32_16x16x32_bf16 v[50:53], v[50:53], v[66:69], 0
	ds_read2_b64 v[66:69], v143 offset0:104 offset1:108
	s_waitcnt lgkmcnt(0)
	v_mfma_f32_16x16x32_bf16 v[50:53], v[66:69], v[70:73], v[50:53]
	ds_read2_b64 v[66:69], v143 offset0:112 offset1:116
	s_waitcnt lgkmcnt(0)
	v_mfma_f32_16x16x32_bf16 v[50:53], v[66:69], v[100:103], v[50:53]
	ds_read2_b64 v[66:69], v143 offset0:120 offset1:124
	v_lshl_add_u64 v[102:103], v[98:99], 0, s[34:35]
	v_lshl_add_u64 v[100:101], v[96:97], 0, s[34:35]
	s_waitcnt lgkmcnt(0)
	v_mfma_f32_16x16x32_bf16 v[70:73], v[66:69], v[144:147], v[50:53]
	v_add_u32_e32 v66, v93, v108
	s_nop 1
	v_add_u32_e32 v67, 0x13c00, v93
	ds_read_b128 v[50:53], v66 offset:34816
	ds_read_b128 v[162:165], v66 offset:34880
	ds_read_b128 v[166:169], v67
	s_add_u32 s34, s34, 0xc8000
	s_addc_u32 s35, s35, 0
	s_cmp_lg_u32 s34, 0x320000
	ds_read_b128 v[170:173], v66 offset:37120
	ds_read_b128 v[174:177], v66 offset:37184
	ds_read_b128 v[178:181], v67 offset:64
	s_waitcnt lgkmcnt(3)
	v_mfma_f32_16x16x32_bf16 v[6:9], v[50:53], v[46:49], v[6:9]
	v_mfma_f32_16x16x32_bf16 v[6:9], v[162:165], v[42:45], v[6:9]
	s_nop 7
	v_pk_mul_f32 v[8:9], v[8:9], v[168:169]
	v_pk_mul_f32 v[6:7], v[6:7], v[166:167]
	ds_read_b128 v[50:53], v66 offset:39424
	ds_read_b128 v[162:165], v66 offset:39488
	ds_read_b128 v[166:169], v67 offset:128
	s_waitcnt lgkmcnt(3)
	v_mfma_f32_16x16x32_bf16 v[10:13], v[170:173], v[46:49], v[10:13]
	v_mfma_f32_16x16x32_bf16 v[10:13], v[174:177], v[42:45], v[10:13]
	s_nop 7
	v_pk_mul_f32 v[12:13], v[12:13], v[180:181]
	v_pk_mul_f32 v[10:11], v[10:11], v[178:179]
	ds_read_b128 v[170:173], v66 offset:41728
	ds_read_b128 v[174:177], v66 offset:41792
	ds_read_b128 v[178:181], v67 offset:192
	s_waitcnt lgkmcnt(3)
	v_mfma_f32_16x16x32_bf16 v[2:5], v[50:53], v[46:49], v[2:5]
	v_mfma_f32_16x16x32_bf16 v[2:5], v[162:165], v[42:45], v[2:5]
	s_nop 7
	v_pk_mul_f32 v[4:5], v[4:5], v[168:169]
	v_pk_mul_f32 v[2:3], v[2:3], v[166:167]
	ds_read_b128 v[50:53], v66 offset:44032
	ds_read_b128 v[162:165], v66 offset:44096
	ds_read_b128 v[166:169], v67 offset:256
	s_waitcnt lgkmcnt(3)
	v_mfma_f32_16x16x32_bf16 v[18:21], v[170:173], v[46:49], v[18:21]
	v_mfma_f32_16x16x32_bf16 v[18:21], v[174:177], v[42:45], v[18:21]
	s_nop 7
	v_pk_mul_f32 v[20:21], v[20:21], v[180:181]
	v_pk_mul_f32 v[18:19], v[18:19], v[178:179]
	ds_read_b128 v[170:173], v66 offset:46336
	ds_read_b128 v[174:177], v66 offset:46400
	ds_read_b128 v[178:181], v67 offset:320
	s_waitcnt lgkmcnt(3)
; #define LAS __attribute__((address_space(3)))
; #define MFMA16(a, b, c) __builtin_amdgcn_mfma_f32_16x16x32_bf16((a), (b), (c), 0, 0, 0)
; template <bool OUT> DI void hgrn_item(LAS unsigned char* lds, bf16_t* proj, float* hst, float* hdv, const float* normw, int item, bool dry) {
;     ...
;         for (int dt = 0; dt < 8; ++dt) {
; #pragma unroll
;             for (int ks = 0; ks < 2; ++ks) { const bf16x8 ka = *(const LAS bf16x8*)(KtT + (16 * dt + e16) * TP + 32 * ks + 8 * rq); st[dt] = MFMA16(ka, vfr[ks], st[dt]); }
;             const f32x4 dv = *(const LAS f32x4*)(Dv + 16 * dt + 4 * rq);
;             st[dt] *= dv;
;         }
;         u32x4 gate8[2];
;         if (OUT) {
; #pragma unroll
;             for (int j = 0; j < 2; ++j) { const int cch = tid + 512 * j; gate8[j] = *(const u32x4*)(proj + (row0 + (cch >> 4)) * NPJ + C_HG + h * 128 + 8 * (cch & 15)); }
;         }
;         __syncthreads();
;         if (OUT) {
; #pragma unroll
;             for (int ti = 0; ti < 4; ++ti)
; #pragma unroll
;                 for (int ks = 0; ks < 2; ++ks) if (2 * ks <= ti) { const bf16x8 aa = *(const LAS bf16x8*)(Ab + (16 * ti + e16) * TP + 32 * ks + 8 * rq); o[ti] = MFMA16(aa, vfr[ks], o[ti]); }
;             LAS float* Ob = (LAS float*)(lds + HOB_OFF);
; #pragma unroll
;             for (int ti = 0; ti < 4; ++ti)
; #pragma unroll
;                 for (int r = 0; r < 4; ++r) Ob[(16 * ti + 4 * rq + r) * OBP + w * 16 + e16] = o[ti][r];
	v_mfma_f32_16x16x32_bf16 v[14:17], v[50:53], v[46:49], v[14:17]
	v_mfma_f32_16x16x32_bf16 v[14:17], v[162:165], v[42:45], v[14:17]
	s_nop 7
	v_pk_mul_f32 v[16:17], v[16:17], v[168:169]
	v_pk_mul_f32 v[14:15], v[14:15], v[166:167]
	ds_read_b128 v[50:53], v66 offset:48640
	ds_read_b128 v[162:165], v66 offset:48704
	ds_read_b128 v[166:169], v67 offset:384
	s_waitcnt lgkmcnt(3)
	v_mfma_f32_16x16x32_bf16 v[26:29], v[170:173], v[46:49], v[26:29]
	v_mfma_f32_16x16x32_bf16 v[26:29], v[174:177], v[42:45], v[26:29]
	s_nop 7
	v_pk_mul_f32 v[28:29], v[28:29], v[180:181]
	v_pk_mul_f32 v[26:27], v[26:27], v[178:179]
	ds_read_b128 v[170:173], v66 offset:50944
	ds_read_b128 v[174:177], v66 offset:51008
	ds_read_b128 v[178:181], v67 offset:448
	s_waitcnt lgkmcnt(3)
	v_mfma_f32_16x16x32_bf16 v[22:25], v[50:53], v[46:49], v[22:25]
	v_mfma_f32_16x16x32_bf16 v[22:25], v[162:165], v[42:45], v[22:25]
	s_nop 7
	v_pk_mul_f32 v[24:25], v[24:25], v[168:169]
	v_pk_mul_f32 v[22:23], v[22:23], v[166:167]
	s_waitcnt lgkmcnt(0)
	v_mfma_f32_16x16x32_bf16 v[30:33], v[170:173], v[46:49], v[30:33]
	v_mfma_f32_16x16x32_bf16 v[30:33], v[174:177], v[42:45], v[30:33]
	s_nop 7
	v_pk_mul_f32 v[32:33], v[32:33], v[180:181]
	v_pk_mul_f32 v[30:31], v[30:31], v[178:179]
	v_add_co_u32_e32 v50, vcc, s47, v102
	s_nop 0
	v_addc_co_u32_e32 v51, vcc, 0, v103, vcc
	global_load_dwordx4 v[66:69], v[50:51], off offset:512
	v_add_co_u32_e32 v50, vcc, s47, v100
	s_nop 1
	v_addc_co_u32_e32 v51, vcc, 0, v101, vcc
	global_load_dwordx4 v[50:53], v[50:51], off offset:512
	s_barrier
	ds_read_b128 v[144:147], v116
	ds_read_b128 v[162:165], v116 offset:2304
	ds_read_b128 v[166:169], v116 offset:4608
	ds_read_b128 v[170:173], v116 offset:4672
	ds_read_b128 v[174:177], v116 offset:6912
	ds_read_b128 v[178:181], v116 offset:6976
	s_waitcnt lgkmcnt(5)
	v_mfma_f32_16x16x32_bf16 v[54:57], v[144:147], v[46:49], v[54:57]
	s_waitcnt lgkmcnt(4)
	v_mfma_f32_16x16x32_bf16 v[58:61], v[162:165], v[46:49], v[58:61]
	s_waitcnt lgkmcnt(3)
	v_mfma_f32_16x16x32_bf16 v[62:65], v[166:169], v[46:49], v[62:65]
	s_waitcnt lgkmcnt(2)
	v_mfma_f32_16x16x32_bf16 v[62:65], v[170:173], v[42:45], v[62:65]
	s_waitcnt lgkmcnt(1)
	v_mfma_f32_16x16x32_bf16 v[46:49], v[174:177], v[46:49], v[70:73]
	s_nop 2
	ds_write2_b32 v125, v54, v55 offset1:132
	s_waitcnt lgkmcnt(1)
	v_mfma_f32_16x16x32_bf16 v[42:45], v[178:181], v[42:45], v[46:49]
	s_nop 2
	v_add_u32_e32 v46, 0x400, v125
	ds_write2_b32 v46, v56, v57 offset0:8 offset1:140
	v_add_u32_e32 v46, 0x2000, v125
	ds_write2_b32 v46, v58, v59 offset0:64 offset1:196
	v_add_u32_e32 v46, 0x2400, v125
	ds_write2_b32 v46, v60, v61 offset0:72 offset1:204
	v_add_u32_e32 v46, 0x4200, v125
	ds_write2_b32 v46, v62, v63 offset1:132
	v_add_u32_e32 v46, 0x4600, v125
	ds_write2_b32 v46, v64, v65 offset0:8 offset1:140
	v_add_u32_e32 v46, 0x6200, v125
	ds_write2_b32 v46, v42, v43 offset0:64 offset1:196
	v_add_u32_e32 v42, 0x6600, v125
	ds_write2_b32 v42, v44, v45 offset0:72 offset1:204
	s_waitcnt lgkmcnt(0)
	s_barrier
; #define LAS __attribute__((address_space(3)))
; DI float bflo(unsigned w) { return __uint_as_float(w << 16); }
; DI float bfhi(unsigned w) { return __uint_as_float(w & 0xffff0000u); }
; DI u32x4 pack8(f32x4 a, f32x4 b) { u32x4 w; w.x = pk2(a[0], a[1]); w.y = pk2(a[2], a[3]); w.z = pk2(b[0], b[1]); w.w = pk2(b[2], b[3]); return w; }
; template <bool OUT> DI void hgrn_item(LAS unsigned char* lds, bf16_t* proj, float* hst, float* hdv, const float* normw, int item, bool dry) {
;     ...
; #pragma unroll
;             for (int j = 0; j < 2; ++j) { const int cch = tid + 512 * j, tt = cch >> 4, e0 = 8 * (cch & 15);
;                 const f32x4 a0 = *(const LAS f32x4*)(Ob + tt * OBP + e0), a1 = *(const LAS f32x4*)(Ob + tt * OBP + e0 + 4);
;                 float q = (a0[0] * a0[0] + a0[1] * a0[1]) + (a0[2] * a0[2] + a0[3] * a0[3]) + (a1[0] * a1[0] + a1[1] * a1[1]) + (a1[2] * a1[2] + a1[3] * a1[3]);
;                 q += __shfl_xor(q, 1); q += __shfl_xor(q, 2); q += __shfl_xor(q, 4); q += __shfl_xor(q, 8);
;                 const float rs = __builtin_amdgcn_rsqf(q * (1.0f / 128.0f) + 1e-6f);
;                 const f32x4 n0 = *(const f32x4*)(normw + e0), n1 = *(const f32x4*)(normw + e0 + 4); const u32x4 g = gate8[j];
;                 f32x4 y0, y1;
;                 y0[0] = a0[0] * rs * n0[0] * bflo(g.x); y0[1] = a0[1] * rs * n0[1] * bfhi(g.x); y0[2] = a0[2] * rs * n0[2] * bflo(g.y); y0[3] = a0[3] * rs * n0[3] * bfhi(g.y);
;                 y1[0] = a1[0] * rs * n1[0] * bflo(g.z); y1[1] = a1[1] * rs * n1[1] * bfhi(g.z); y1[2] = a1[2] * rs * n1[2] * bflo(g.w); y1[3] = a1[3] * rs * n1[3] * bfhi(g.w);
;                 if (!dry) *(u32x4*)(proj + (row0 + tt) * NPJ + C_HQ + h * 128 + e0) = pack8(y0, y1); }
	ds_read_b128 v[42:45], v117
	ds_read_b128 v[46:49], v117 offset:16
	s_waitcnt vmcnt(1)
	v_lshlrev_b32_e32 v64, 16, v68
	v_and_b32_e32 v65, 0xffff0000, v68
	s_waitcnt lgkmcnt(1)
	v_pk_mul_f32 v[54:55], v[44:45], v[44:45]
	v_pk_mul_f32 v[56:57], v[42:43], v[42:43]
	s_nop 0
	v_pk_mov_b32 v[58:59], v[56:57], v[54:55] op_sel:[1,0]
	v_mov_b32_e32 v57, v55
	v_pk_add_f32 v[54:55], v[58:59], v[56:57]
	s_waitcnt lgkmcnt(0)
	v_pk_mul_f32 v[56:57], v[48:49], v[48:49]
	v_pk_mul_f32 v[58:59], v[46:47], v[46:47]
	v_mov_b32_e32 v60, v56
	v_mov_b32_e32 v61, v58
	v_mov_b32_e32 v58, v57
	v_pk_add_f32 v[56:57], v[60:61], v[58:59]
	v_add_f32_e32 v54, v54, v55
	v_add_f32_e32 v54, v54, v57
	v_add_f32_e32 v54, v56, v54
	s_nop 1
	v_add_f32_dpp v54, v54, v54 quad_perm:[1,0,3,2] row_mask:0xf bank_mask:0xf
	s_nop 1
	v_add_f32_dpp v54, v54, v54 quad_perm:[2,3,0,1] row_mask:0xf bank_mask:0xf
	s_nop 1
	v_add_f32_dpp v62, v54, v54 row_half_mirror row_mask:0xf bank_mask:0xf
	s_nop 1
	v_add_f32_dpp v62, v62, v62 row_mirror row_mask:0xf bank_mask:0xf
	v_fmamk_f32 v62, v62, 0x3c000000, v118
	v_rsq_f32_e32 v62, v62
	s_nop 0
	v_pk_mul_f32 v[46:47], v[46:47], v[62:63] op_sel_hi:[1,0]
	v_pk_mul_f32 v[48:49], v[48:49], v[62:63] op_sel_hi:[1,0]
	v_pk_mul_f32 v[42:43], v[42:43], v[62:63] op_sel_hi:[1,0]
	v_pk_mul_f32 v[44:45], v[44:45], v[62:63] op_sel_hi:[1,0]
	s_waitcnt vmcnt(0)
	v_pk_mul_f32 v[42:43], v[232:233], v[42:43]
	v_pk_mul_f32 v[46:47], v[236:237], v[46:47]
	v_lshlrev_b32_e32 v58, 16, v69
	v_and_b32_e32 v59, 0xffff0000, v69
	v_pk_mul_f32 v[48:49], v[238:239], v[48:49]
	v_lshlrev_b32_e32 v54, 16, v67
	v_pk_mul_f32 v[48:49], v[48:49], v[58:59]
	v_lshlrev_b32_e32 v58, 16, v66
	v_and_b32_e32 v59, 0xffff0000, v66
	v_and_b32_e32 v55, 0xffff0000, v67
	v_pk_mul_f32 v[44:45], v[234:235], v[44:45]
	v_pk_mul_f32 v[46:47], v[46:47], v[64:65]
	v_pk_mul_f32 v[42:43], v[42:43], v[58:59]
	v_pk_mul_f32 v[44:45], v[44:45], v[54:55]
	v_cvt_pk_bf16_f32 v42, v42, v43
	v_cvt_pk_bf16_f32 v43, v44, v45
	v_cvt_pk_bf16_f32 v44, v46, v47
	v_cvt_pk_bf16_f32 v45, v48, v49
	global_store_dwordx4 v[102:103], v[42:45], off offset:1536
	ds_read_b128 v[42:45], v119
	ds_read_b128 v[46:49], v119 offset:16
	v_lshlrev_b32_e32 v64, 16, v52
	v_and_b32_e32 v65, 0xffff0000, v52
	v_lshlrev_b32_e32 v52, 16, v53
	s_waitcnt lgkmcnt(1)
	v_pk_mul_f32 v[54:55], v[44:45], v[44:45]
	v_pk_mul_f32 v[56:57], v[42:43], v[42:43]
	v_and_b32_e32 v53, 0xffff0000, v53
	v_pk_mov_b32 v[58:59], v[56:57], v[54:55] op_sel:[1,0]
	v_mov_b32_e32 v57, v55
	v_pk_add_f32 v[54:55], v[58:59], v[56:57]
	s_waitcnt lgkmcnt(0)
	v_pk_mul_f32 v[56:57], v[48:49], v[48:49]
	v_pk_mul_f32 v[58:59], v[46:47], v[46:47]
	v_mov_b32_e32 v60, v56
	v_mov_b32_e32 v61, v58
	v_mov_b32_e32 v58, v57
	v_pk_add_f32 v[56:57], v[60:61], v[58:59]
	v_add_f32_e32 v54, v54, v55
	v_add_f32_e32 v54, v54, v57
	v_add_f32_e32 v54, v56, v54
	s_nop 1
	v_add_f32_dpp v54, v54, v54 quad_perm:[1,0,3,2] row_mask:0xf bank_mask:0xf
	s_nop 1
	v_add_f32_dpp v54, v54, v54 quad_perm:[2,3,0,1] row_mask:0xf bank_mask:0xf
	s_nop 1
	v_add_f32_dpp v62, v54, v54 row_half_mirror row_mask:0xf bank_mask:0xf
	s_nop 1
	v_add_f32_dpp v62, v62, v62 row_mirror row_mask:0xf bank_mask:0xf
	v_fmamk_f32 v62, v62, 0x3c000000, v118
	v_rsq_f32_e32 v62, v62
	s_nop 0
	v_pk_mul_f32 v[48:49], v[48:49], v[62:63] op_sel_hi:[1,0]
	v_pk_mul_f32 v[46:47], v[46:47], v[62:63] op_sel_hi:[1,0]
	v_pk_mul_f32 v[42:43], v[42:43], v[62:63] op_sel_hi:[1,0]
	v_pk_mul_f32 v[44:45], v[44:45], v[62:63] op_sel_hi:[1,0]
	v_pk_mul_f32 v[42:43], v[232:233], v[42:43]
	v_pk_mul_f32 v[48:49], v[238:239], v[48:49]
	v_pk_mul_f32 v[46:47], v[236:237], v[46:47]
	v_pk_mul_f32 v[48:49], v[48:49], v[52:53]
	v_lshlrev_b32_e32 v52, 16, v50
	v_and_b32_e32 v53, 0xffff0000, v50
	v_lshlrev_b32_e32 v50, 16, v51
	v_and_b32_e32 v51, 0xffff0000, v51
	v_pk_mul_f32 v[44:45], v[234:235], v[44:45]
	v_pk_mul_f32 v[46:47], v[46:47], v[64:65]
	v_pk_mul_f32 v[42:43], v[42:43], v[52:53]
	v_pk_mul_f32 v[44:45], v[44:45], v[50:51]
	v_cvt_pk_bf16_f32 v42, v42, v43
	v_cvt_pk_bf16_f32 v43, v44, v45
	v_cvt_pk_bf16_f32 v44, v46, v47
	v_cvt_pk_bf16_f32 v45, v48, v49
	global_store_dwordx4 v[100:101], v[42:45], off offset:1536
	s_waitcnt vmcnt(1)
	v_lshl_or_b32 v129, v185, 16, v184
	v_lshl_or_b32 v127, v190, 16, v191
	v_lshl_or_b32 v131, v192, 16, v188
	v_lshl_or_b32 v128, v194, 16, v189
	v_lshl_or_b32 v133, v196, 16, v195
	v_lshl_or_b32 v135, v203, 16, v202
	v_lshl_or_b32 v134, v214, 16, v215
	v_lshl_or_b32 v34, v187, 16, v186
	v_lshl_or_b32 v35, v199, 16, v193
	v_lshl_or_b32 v36, v200, 16, v197
	v_lshl_or_b32 v130, v198, 16, v201
	v_lshl_or_b32 v37, v205, 16, v204
	v_lshl_or_b32 v132, v206, 16, v207
	v_lshl_or_b32 v137, v209, 16, v208
	v_lshl_or_b32 v38, v211, 16, v210
	v_lshl_or_b32 v139, v216, 16, v212
	v_lshl_or_b32 v136, v218, 16, v213
	v_lshl_or_b32 v141, v220, 16, v219
	v_lshl_or_b32 v39, v223, 16, v217
	v_lshl_or_b32 v40, v224, 16, v221
	v_lshl_or_b32 v138, v222, 16, v225
	v_lshl_or_b32 v142, v227, 16, v226
	v_lshl_or_b32 v41, v229, 16, v228
	v_lshl_or_b32 v140, v230, 16, v231
	v_mov_b32_e32 v46, v127
	v_mov_b32_e32 v47, v128
	v_mov_b32_e32 v49, v130
	v_mov_b32_e32 v51, v132
	v_mov_b32_e32 v52, v134
	v_mov_b32_e32 v53, v136
	v_mov_b32_e32 v54, v138
	v_mov_b32_e32 v48, v140
	v_mov_b32_e32 v42, v129
	v_mov_b32_e32 v43, v131
	v_mov_b32_e32 v44, v133
	v_mov_b32_e32 v45, v135
	v_mov_b32_e32 v50, v137
	v_mov_b32_e32 v55, v139
	v_mov_b32_e32 v56, v141
	v_mov_b32_e32 v57, v142
	s_cbranch_scc0 .LBB0_1168
